# p7epi
# speedup vs baseline: 1.0024x; 1.0024x over previous
; __device__ __forceinline__ float bf_lo(u32 v) { return __uint_as_float(v << 16); }
; __device__ __forceinline__ void row_stats(const float* st, int row, float& mu, float& rstd) {
;   float2 v = *(const float2*)(st + (size_t)row * 2);
;   mu = v.x * (1.0f / DM);
;   float var = fmaxf(v.y * (1.0f / DM) - mu * mu, 0.f);
;   rstd = rsqrtf(var + LN_EPS);
; }
; template <int EPI>
; __device__ __forceinline__ void gemm_phase(const u16* __restrict__ A, const u16* __restrict__ Bt, const int K,
;                                            const int nN, char* shm, const EpiArgs& ea) {
;     ...
;               float mu = 0.f, rstd = 1.f;
;               if (EPI != EPI_FFN1) row_stats(ea.st_in, row, mu, rstd);
;               float rs = 0.f, rq = 0.f;
; #pragma unroll
;               for (int bj = 0; bj < 2; ++bj) {
;                 uint2 pk[2];
; #pragma unroll
;                 for (int n = 0; n < 2; ++n) {
;                   const int col = cb + bj * 128 + n * 16;
;                   f32x4 c = acc[ai][bj][m][n];
;                   float h[4];
;                   if (EPI == EPI_FFN1) {
;                     float4 rv = *(const float4*)(ea.res + (size_t)row * DM + col);
;                     h[0] = rv.x; h[1] = rv.y; h[2] = rv.z; h[3] = rv.w;
;                   } else {
;                     uint2 yv = *(const uint2*)((const char*)ea.yb + tl_off(row, col, DM >> 6));
;                     float4 gv = *(const float4*)(ea.lng + col);
;                     float4 bv = *(const float4*)(ea.lnb + col);
;                     h[0] = (bf_lo(yv.x) - mu) * rstd * gv.x + bv.x; h[1] = (bf_hi(yv.x) - mu) * rstd * gv.y + bv.y;
;                     h[2] = (bf_lo(yv.y) - mu) * rstd * gv.z + bv.z; h[3] = (bf_hi(yv.y) - mu) * rstd * gv.w + bv.w;
;                   }
;                   float y[4];
;                   if (EPI == EPI_OUT) {
;                     float4 bo = *(const float4*)(ea.bias + col);
;                     y[0] = ALPHA * h[0] + c[0] + bo.x; y[1] = ALPHA * h[1] + c[1] + bo.y;
;                     y[2] = ALPHA * h[2] + c[2] + bo.z; y[3] = ALPHA * h[3] + c[3] + bo.w;
;                   } else {
; #pragma unroll
;                     for (int j = 0; j < 4; ++j) y[j] = ALPHA * h[j] + 0.5f * c[j];
;                   }
;                   if (EPI == EPI_FFN2) {
;                     *(float4*)(ea.outf + (size_t)row * DM + col) = make_float4(y[0], y[1], y[2], y[3]);
.LBB0_625:
	s_lshr_b32 s98, s33, 7
	s_mul_i32 s98, s98, 0x84000
	s_lshr_b32 s99, s47, 6
	s_lshl_b32 s99, s99, 14
	s_add_i32 s98, s98, s99
	v_add_u32_e32 v170, s33, v139
	v_add_u32_e32 v171, s47, v140
	v_lshlrev_b32_e32 v172, 3, v170
	v_lshlrev_b32_e32 v173, 2, v171
	global_load_dwordx2 v[150:151], v172, s[8:9]
	global_load_dwordx2 v[152:153], v172, s[8:9] offset:128
	global_load_dwordx2 v[154:155], v172, s[8:9] offset:256
	global_load_dwordx2 v[156:157], v172, s[8:9] offset:384
	global_load_dwordx2 v[158:159], v172, s[8:9] offset:1024
	global_load_dwordx2 v[160:161], v172, s[8:9] offset:1152
	global_load_dwordx2 v[162:163], v172, s[8:9] offset:1280
	global_load_dwordx2 v[164:165], v172, s[8:9] offset:1408
	global_load_dwordx4 v[176:179], v173, s[22:23]
	global_load_dwordx4 v[192:195], v173, s[76:77]
	global_load_dwordx4 v[180:183], v173, s[22:23] offset:64
	global_load_dwordx4 v[196:199], v173, s[76:77] offset:64
	global_load_dwordx4 v[184:187], v173, s[22:23] offset:512
	global_load_dwordx4 v[200:203], v173, s[76:77] offset:512
	global_load_dwordx4 v[188:191], v173, s[22:23] offset:576
	global_load_dwordx4 v[204:207], v173, s[76:77] offset:576
	v_and_b32_e32 v132, 15, v174
	v_lshlrev_b32_e32 v130, 6, v132
	v_and_b32_e32 v132, 48, v174
	v_lshrrev_b32_e32 v132, 1, v132
	v_or_b32_e32 v130, v130, v132
	v_and_b32_e32 v132, 64, v174
	v_lshl_or_b32 v130, v132, 4, v130
	v_and_b32_e32 v132, 0x80, v174
	v_lshl_or_b32 v130, v132, 7, v130
	v_and_b32_e32 v132, 0x100, v174
	v_lshl_or_b32 v130, v132, 5, v130
	v_add_u32_e32 v130, s98, v130
	v_and_b32_e32 v175, 8, v174
	v_lshlrev_b32_e32 v175, 2, v175
	v_sub_u32_e32 v131, v130, v175
	v_add_u32_e32 v131, 32, v131
	v_add_u32_e32 v130, v130, v175
	v_lshl_add_u32 v128, v170, 13, v173
	global_load_dwordx2 v[208:209], v130, s[10:11]
	global_load_dwordx2 v[210:211], v131, s[10:11]
	v_add_u32_e32 v132, 0x8000, v130
	global_load_dwordx2 v[212:213], v132, s[10:11]
	v_add_u32_e32 v149, 0x8000, v131
	global_load_dwordx2 v[214:215], v149, s[10:11]
	v_add_u32_e32 v132, 0x800, v130
	global_load_dwordx2 v[216:217], v132, s[10:11]
	v_add_u32_e32 v149, 0x800, v131
	global_load_dwordx2 v[218:219], v149, s[10:11]
	v_add_u32_e32 v132, 0x8800, v130
	global_load_dwordx2 v[220:221], v132, s[10:11]
	v_add_u32_e32 v149, 0x8800, v131
	global_load_dwordx2 v[222:223], v149, s[10:11]
	v_add_u32_e32 v132, 0x1000, v130
	global_load_dwordx2 v[224:225], v132, s[10:11]
	v_add_u32_e32 v149, 0x1000, v131
	global_load_dwordx2 v[226:227], v149, s[10:11]
	v_add_u32_e32 v132, 0x9000, v130
	global_load_dwordx2 v[228:229], v132, s[10:11]
	v_add_u32_e32 v149, 0x9000, v131
	global_load_dwordx2 v[230:231], v149, s[10:11]
	v_add_u32_e32 v132, 0x1800, v130
	global_load_dwordx2 v[232:233], v132, s[10:11]
	v_add_u32_e32 v149, 0x1800, v131
	global_load_dwordx2 v[234:235], v149, s[10:11]
	v_add_u32_e32 v132, 0x9800, v130
	global_load_dwordx2 v[236:237], v132, s[10:11]
	v_add_u32_e32 v149, 0x9800, v131
	global_load_dwordx2 v[238:239], v149, s[10:11]
	s_waitcnt vmcnt(31)
	v_pk_mul_f32 v[150:151], v[150:151], s[16:17] op_sel_hi:[1,0]
	v_mov_b32_e32 v133, v128
	v_fma_f32 v166, -v150, v150, v151
	v_max_f32_e32 v166, 0, v166
	v_add_f32_e32 v166, 0x3727c5ac, v166
	v_rsq_f32_e32 v166, v166
	s_nop 0
	s_waitcnt vmcnt(16)
	s_waitcnt vmcnt(15)
	v_lshlrev_b32_e32 v134, 16, v208
	v_and_b32_e32 v135, 0xffff0000, v208
	v_lshlrev_b32_e32 v136, 16, v209
	v_and_b32_e32 v137, 0xffff0000, v209
	v_pk_add_f32 v[134:135], v[134:135], v[150:151] op_sel_hi:[1,0] neg_lo:[0,1] neg_hi:[0,1]
	v_pk_add_f32 v[136:137], v[136:137], v[150:151] op_sel_hi:[1,0] neg_lo:[0,1] neg_hi:[0,1]
	v_pk_mul_f32 v[134:135], v[134:135], v[166:167] op_sel_hi:[1,0]
	v_pk_mul_f32 v[136:137], v[136:137], v[166:167] op_sel_hi:[1,0]
	v_pk_fma_f32 v[134:135], v[176:177], v[134:135], v[192:193]
	v_pk_fma_f32 v[136:137], v[178:179], v[136:137], v[194:195]
	v_pk_mul_f32 v[134:135], v[134:135], s[18:19] op_sel_hi:[1,0]
	v_pk_mul_f32 v[136:137], v[136:137], s[18:19] op_sel_hi:[1,0]
	v_pk_fma_f32 v[124:125], v[124:125], 0.5, v[134:135] op_sel_hi:[1,0,1]
	v_pk_fma_f32 v[126:127], v[126:127], 0.5, v[136:137] op_sel_hi:[1,0,1]
	global_store_dwordx4 v133, v[124:127], s[88:89]
	s_waitcnt vmcnt(15)
	v_lshlrev_b32_e32 v240, 16, v210
	v_and_b32_e32 v241, 0xffff0000, v210
	v_lshlrev_b32_e32 v242, 16, v211
	v_and_b32_e32 v243, 0xffff0000, v211
	v_pk_add_f32 v[240:241], v[240:241], v[150:151] op_sel_hi:[1,0] neg_lo:[0,1] neg_hi:[0,1]
	v_pk_add_f32 v[242:243], v[242:243], v[150:151] op_sel_hi:[1,0] neg_lo:[0,1] neg_hi:[0,1]
	v_pk_mul_f32 v[240:241], v[240:241], v[166:167] op_sel_hi:[1,0]
	v_pk_mul_f32 v[242:243], v[242:243], v[166:167] op_sel_hi:[1,0]
	v_pk_fma_f32 v[240:241], v[180:181], v[240:241], v[196:197]
	v_pk_fma_f32 v[242:243], v[182:183], v[242:243], v[198:199]
	v_pk_mul_f32 v[240:241], v[240:241], s[18:19] op_sel_hi:[1,0]
	v_pk_mul_f32 v[242:243], v[242:243], s[18:19] op_sel_hi:[1,0]
	v_pk_fma_f32 v[120:121], v[120:121], 0.5, v[240:241] op_sel_hi:[1,0,1]
	v_pk_fma_f32 v[122:123], v[122:123], 0.5, v[242:243] op_sel_hi:[1,0,1]
	global_store_dwordx4 v133, v[120:123], s[88:89] offset:64
	s_waitcnt vmcnt(15)
	v_lshlrev_b32_e32 v134, 16, v212
	v_and_b32_e32 v135, 0xffff0000, v212
	v_lshlrev_b32_e32 v136, 16, v213
	v_and_b32_e32 v137, 0xffff0000, v213
	v_pk_add_f32 v[134:135], v[134:135], v[150:151] op_sel_hi:[1,0] neg_lo:[0,1] neg_hi:[0,1]
	v_pk_add_f32 v[136:137], v[136:137], v[150:151] op_sel_hi:[1,0] neg_lo:[0,1] neg_hi:[0,1]
	v_pk_mul_f32 v[134:135], v[134:135], v[166:167] op_sel_hi:[1,0]
	v_pk_mul_f32 v[136:137], v[136:137], v[166:167] op_sel_hi:[1,0]
	v_pk_fma_f32 v[134:135], v[184:185], v[134:135], v[200:201]
	v_pk_fma_f32 v[136:137], v[186:187], v[136:137], v[202:203]
	v_pk_mul_f32 v[134:135], v[134:135], s[18:19] op_sel_hi:[1,0]
	v_pk_mul_f32 v[136:137], v[136:137], s[18:19] op_sel_hi:[1,0]
	v_pk_fma_f32 v[116:117], v[116:117], 0.5, v[134:135] op_sel_hi:[1,0,1]
	v_pk_fma_f32 v[118:119], v[118:119], 0.5, v[136:137] op_sel_hi:[1,0,1]
	global_store_dwordx4 v133, v[116:119], s[88:89] offset:512
	s_waitcnt vmcnt(15)
; __device__ __forceinline__ float bf_lo(u32 v) { return __uint_as_float(v << 16); }
; __device__ __forceinline__ float bf_hi(u32 v) { return __uint_as_float(v & 0xFFFF0000u); }
; template <int EPI>
; __device__ __forceinline__ void gemm_phase(const u16* __restrict__ A, const u16* __restrict__ Bt, const int K,
;                                            const int nN, char* shm, const EpiArgs& ea) {
;     ...
;                   const int col = cb + bj * 128 + n * 16;
;                   f32x4 c = acc[ai][bj][m][n];
;                   float h[4];
;                   if (EPI == EPI_FFN1) {
;                     float4 rv = *(const float4*)(ea.res + (size_t)row * DM + col);
;                     h[0] = rv.x; h[1] = rv.y; h[2] = rv.z; h[3] = rv.w;
;                   } else {
;                     uint2 yv = *(const uint2*)((const char*)ea.yb + tl_off(row, col, DM >> 6));
;                     float4 gv = *(const float4*)(ea.lng + col);
;                     float4 bv = *(const float4*)(ea.lnb + col);
;                     h[0] = (bf_lo(yv.x) - mu) * rstd * gv.x + bv.x; h[1] = (bf_hi(yv.x) - mu) * rstd * gv.y + bv.y;
;                     h[2] = (bf_lo(yv.y) - mu) * rstd * gv.z + bv.z; h[3] = (bf_hi(yv.y) - mu) * rstd * gv.w + bv.w;
;                   }
;                   float y[4];
;                   if (EPI == EPI_OUT) {
;                     float4 bo = *(const float4*)(ea.bias + col);
;                     y[0] = ALPHA * h[0] + c[0] + bo.x; y[1] = ALPHA * h[1] + c[1] + bo.y;
;                     y[2] = ALPHA * h[2] + c[2] + bo.z; y[3] = ALPHA * h[3] + c[3] + bo.w;
;                   } else {
; #pragma unroll
;                     for (int j = 0; j < 4; ++j) y[j] = ALPHA * h[j] + 0.5f * c[j];
;                   }
;                   if (EPI == EPI_FFN2) {
;                     *(float4*)(ea.outf + (size_t)row * DM + col) = make_float4(y[0], y[1], y[2], y[3]);
	v_lshlrev_b32_e32 v240, 16, v214
	v_and_b32_e32 v241, 0xffff0000, v214
	v_lshlrev_b32_e32 v242, 16, v215
	v_and_b32_e32 v243, 0xffff0000, v215
	v_pk_add_f32 v[240:241], v[240:241], v[150:151] op_sel_hi:[1,0] neg_lo:[0,1] neg_hi:[0,1]
	v_pk_add_f32 v[242:243], v[242:243], v[150:151] op_sel_hi:[1,0] neg_lo:[0,1] neg_hi:[0,1]
	v_pk_mul_f32 v[240:241], v[240:241], v[166:167] op_sel_hi:[1,0]
	v_pk_mul_f32 v[242:243], v[242:243], v[166:167] op_sel_hi:[1,0]
	v_pk_fma_f32 v[240:241], v[188:189], v[240:241], v[204:205]
	v_pk_fma_f32 v[242:243], v[190:191], v[242:243], v[206:207]
	v_pk_mul_f32 v[240:241], v[240:241], s[18:19] op_sel_hi:[1,0]
	v_pk_mul_f32 v[242:243], v[242:243], s[18:19] op_sel_hi:[1,0]
	v_pk_fma_f32 v[112:113], v[112:113], 0.5, v[240:241] op_sel_hi:[1,0,1]
	v_pk_fma_f32 v[114:115], v[114:115], 0.5, v[242:243] op_sel_hi:[1,0,1]
	global_store_dwordx4 v133, v[112:115], s[88:89] offset:576
	v_add_u32_e32 v132, 0x84000, v130
	global_load_dwordx2 v[208:209], v132, s[10:11]
	v_add_u32_e32 v149, 0x84000, v131
	global_load_dwordx2 v[210:211], v149, s[10:11]
	v_add_u32_e32 v132, 0x8c000, v130
	global_load_dwordx2 v[212:213], v132, s[10:11]
	v_add_u32_e32 v149, 0x8c000, v131
	global_load_dwordx2 v[214:215], v149, s[10:11]
	v_pk_mul_f32 v[152:153], v[152:153], s[16:17] op_sel_hi:[1,0]
	v_add_u32_e32 v133, 0x20000, v128
	v_fma_f32 v168, -v152, v152, v153
	v_max_f32_e32 v168, 0, v168
	v_add_f32_e32 v168, 0x3727c5ac, v168
	v_rsq_f32_e32 v168, v168
	s_nop 0
	s_waitcnt vmcnt(19)
	v_lshlrev_b32_e32 v134, 16, v216
	v_and_b32_e32 v135, 0xffff0000, v216
	v_lshlrev_b32_e32 v136, 16, v217
	v_and_b32_e32 v137, 0xffff0000, v217
	v_pk_add_f32 v[134:135], v[134:135], v[152:153] op_sel_hi:[1,0] neg_lo:[0,1] neg_hi:[0,1]
	v_pk_add_f32 v[136:137], v[136:137], v[152:153] op_sel_hi:[1,0] neg_lo:[0,1] neg_hi:[0,1]
	v_pk_mul_f32 v[134:135], v[134:135], v[168:169] op_sel_hi:[1,0]
	v_pk_mul_f32 v[136:137], v[136:137], v[168:169] op_sel_hi:[1,0]
	v_pk_fma_f32 v[134:135], v[176:177], v[134:135], v[192:193]
	v_pk_fma_f32 v[136:137], v[178:179], v[136:137], v[194:195]
	v_pk_mul_f32 v[134:135], v[134:135], s[18:19] op_sel_hi:[1,0]
	v_pk_mul_f32 v[136:137], v[136:137], s[18:19] op_sel_hi:[1,0]
	v_pk_fma_f32 v[108:109], v[108:109], 0.5, v[134:135] op_sel_hi:[1,0,1]
	v_pk_fma_f32 v[110:111], v[110:111], 0.5, v[136:137] op_sel_hi:[1,0,1]
	global_store_dwordx4 v133, v[108:111], s[88:89]
	s_waitcnt vmcnt(19)
	v_lshlrev_b32_e32 v240, 16, v218
	v_and_b32_e32 v241, 0xffff0000, v218
	v_lshlrev_b32_e32 v242, 16, v219
	v_and_b32_e32 v243, 0xffff0000, v219
	v_pk_add_f32 v[240:241], v[240:241], v[152:153] op_sel_hi:[1,0] neg_lo:[0,1] neg_hi:[0,1]
	v_pk_add_f32 v[242:243], v[242:243], v[152:153] op_sel_hi:[1,0] neg_lo:[0,1] neg_hi:[0,1]
	v_pk_mul_f32 v[240:241], v[240:241], v[168:169] op_sel_hi:[1,0]
	v_pk_mul_f32 v[242:243], v[242:243], v[168:169] op_sel_hi:[1,0]
	v_pk_fma_f32 v[240:241], v[180:181], v[240:241], v[196:197]
	v_pk_fma_f32 v[242:243], v[182:183], v[242:243], v[198:199]
	v_pk_mul_f32 v[240:241], v[240:241], s[18:19] op_sel_hi:[1,0]
	v_pk_mul_f32 v[242:243], v[242:243], s[18:19] op_sel_hi:[1,0]
	v_pk_fma_f32 v[104:105], v[104:105], 0.5, v[240:241] op_sel_hi:[1,0,1]
	v_pk_fma_f32 v[106:107], v[106:107], 0.5, v[242:243] op_sel_hi:[1,0,1]
	global_store_dwordx4 v133, v[104:107], s[88:89] offset:64
	s_waitcnt vmcnt(19)
	v_lshlrev_b32_e32 v134, 16, v220
	v_and_b32_e32 v135, 0xffff0000, v220
	v_lshlrev_b32_e32 v136, 16, v221
	v_and_b32_e32 v137, 0xffff0000, v221
	v_pk_add_f32 v[134:135], v[134:135], v[152:153] op_sel_hi:[1,0] neg_lo:[0,1] neg_hi:[0,1]
	v_pk_add_f32 v[136:137], v[136:137], v[152:153] op_sel_hi:[1,0] neg_lo:[0,1] neg_hi:[0,1]
	v_pk_mul_f32 v[134:135], v[134:135], v[168:169] op_sel_hi:[1,0]
	v_pk_mul_f32 v[136:137], v[136:137], v[168:169] op_sel_hi:[1,0]
	v_pk_fma_f32 v[134:135], v[184:185], v[134:135], v[200:201]
	v_pk_fma_f32 v[136:137], v[186:187], v[136:137], v[202:203]
	v_pk_mul_f32 v[134:135], v[134:135], s[18:19] op_sel_hi:[1,0]
	v_pk_mul_f32 v[136:137], v[136:137], s[18:19] op_sel_hi:[1,0]
	v_pk_fma_f32 v[100:101], v[100:101], 0.5, v[134:135] op_sel_hi:[1,0,1]
	v_pk_fma_f32 v[102:103], v[102:103], 0.5, v[136:137] op_sel_hi:[1,0,1]
	global_store_dwordx4 v133, v[100:103], s[88:89] offset:512
	s_waitcnt vmcnt(19)
	v_lshlrev_b32_e32 v240, 16, v222
	v_and_b32_e32 v241, 0xffff0000, v222
	v_lshlrev_b32_e32 v242, 16, v223
	v_and_b32_e32 v243, 0xffff0000, v223
	v_pk_add_f32 v[240:241], v[240:241], v[152:153] op_sel_hi:[1,0] neg_lo:[0,1] neg_hi:[0,1]
	v_pk_add_f32 v[242:243], v[242:243], v[152:153] op_sel_hi:[1,0] neg_lo:[0,1] neg_hi:[0,1]
	v_pk_mul_f32 v[240:241], v[240:241], v[168:169] op_sel_hi:[1,0]
	v_pk_mul_f32 v[242:243], v[242:243], v[168:169] op_sel_hi:[1,0]
	v_pk_fma_f32 v[240:241], v[188:189], v[240:241], v[204:205]
	v_pk_fma_f32 v[242:243], v[190:191], v[242:243], v[206:207]
	v_pk_mul_f32 v[240:241], v[240:241], s[18:19] op_sel_hi:[1,0]
	v_pk_mul_f32 v[242:243], v[242:243], s[18:19] op_sel_hi:[1,0]
	v_pk_fma_f32 v[96:97], v[96:97], 0.5, v[240:241] op_sel_hi:[1,0,1]
	v_pk_fma_f32 v[98:99], v[98:99], 0.5, v[242:243] op_sel_hi:[1,0,1]
	global_store_dwordx4 v133, v[96:99], s[88:89] offset:576
	v_add_u32_e32 v132, 0x84800, v130
	global_load_dwordx2 v[216:217], v132, s[10:11]
	v_add_u32_e32 v149, 0x84800, v131
	global_load_dwordx2 v[218:219], v149, s[10:11]
	v_add_u32_e32 v132, 0x8c800, v130
	global_load_dwordx2 v[220:221], v132, s[10:11]
	v_add_u32_e32 v149, 0x8c800, v131
	global_load_dwordx2 v[222:223], v149, s[10:11]
	v_pk_mul_f32 v[154:155], v[154:155], s[16:17] op_sel_hi:[1,0]
	v_add_u32_e32 v133, 0x40000, v128
	v_fma_f32 v166, -v154, v154, v155
	v_max_f32_e32 v166, 0, v166
	v_add_f32_e32 v166, 0x3727c5ac, v166
	v_rsq_f32_e32 v166, v166
	s_nop 0
	s_waitcnt vmcnt(23)
; __device__ __forceinline__ float bf_lo(u32 v) { return __uint_as_float(v << 16); }
; __device__ __forceinline__ float bf_hi(u32 v) { return __uint_as_float(v & 0xFFFF0000u); }
; template <int EPI>
; __device__ __forceinline__ void gemm_phase(const u16* __restrict__ A, const u16* __restrict__ Bt, const int K,
;                                            const int nN, char* shm, const EpiArgs& ea) {
;     ...
;                   const int col = cb + bj * 128 + n * 16;
;                   f32x4 c = acc[ai][bj][m][n];
;                   float h[4];
;                   if (EPI == EPI_FFN1) {
;                     float4 rv = *(const float4*)(ea.res + (size_t)row * DM + col);
;                     h[0] = rv.x; h[1] = rv.y; h[2] = rv.z; h[3] = rv.w;
;                   } else {
;                     uint2 yv = *(const uint2*)((const char*)ea.yb + tl_off(row, col, DM >> 6));
;                     float4 gv = *(const float4*)(ea.lng + col);
;                     float4 bv = *(const float4*)(ea.lnb + col);
;                     h[0] = (bf_lo(yv.x) - mu) * rstd * gv.x + bv.x; h[1] = (bf_hi(yv.x) - mu) * rstd * gv.y + bv.y;
;                     h[2] = (bf_lo(yv.y) - mu) * rstd * gv.z + bv.z; h[3] = (bf_hi(yv.y) - mu) * rstd * gv.w + bv.w;
;                   }
;                   float y[4];
;                   if (EPI == EPI_OUT) {
;                     float4 bo = *(const float4*)(ea.bias + col);
;                     y[0] = ALPHA * h[0] + c[0] + bo.x; y[1] = ALPHA * h[1] + c[1] + bo.y;
;                     y[2] = ALPHA * h[2] + c[2] + bo.z; y[3] = ALPHA * h[3] + c[3] + bo.w;
;                   } else {
; #pragma unroll
;                     for (int j = 0; j < 4; ++j) y[j] = ALPHA * h[j] + 0.5f * c[j];
;                   }
;                   if (EPI == EPI_FFN2) {
;                     *(float4*)(ea.outf + (size_t)row * DM + col) = make_float4(y[0], y[1], y[2], y[3]);
	v_lshlrev_b32_e32 v134, 16, v224
	v_and_b32_e32 v135, 0xffff0000, v224
	v_lshlrev_b32_e32 v136, 16, v225
	v_and_b32_e32 v137, 0xffff0000, v225
	v_pk_add_f32 v[134:135], v[134:135], v[154:155] op_sel_hi:[1,0] neg_lo:[0,1] neg_hi:[0,1]
	v_pk_add_f32 v[136:137], v[136:137], v[154:155] op_sel_hi:[1,0] neg_lo:[0,1] neg_hi:[0,1]
	v_pk_mul_f32 v[134:135], v[134:135], v[166:167] op_sel_hi:[1,0]
	v_pk_mul_f32 v[136:137], v[136:137], v[166:167] op_sel_hi:[1,0]
	v_pk_fma_f32 v[134:135], v[176:177], v[134:135], v[192:193]
	v_pk_fma_f32 v[136:137], v[178:179], v[136:137], v[194:195]
	v_pk_mul_f32 v[134:135], v[134:135], s[18:19] op_sel_hi:[1,0]
	v_pk_mul_f32 v[136:137], v[136:137], s[18:19] op_sel_hi:[1,0]
	v_pk_fma_f32 v[92:93], v[92:93], 0.5, v[134:135] op_sel_hi:[1,0,1]
	v_pk_fma_f32 v[94:95], v[94:95], 0.5, v[136:137] op_sel_hi:[1,0,1]
	global_store_dwordx4 v133, v[92:95], s[88:89]
	s_waitcnt vmcnt(23)
	v_lshlrev_b32_e32 v240, 16, v226
	v_and_b32_e32 v241, 0xffff0000, v226
	v_lshlrev_b32_e32 v242, 16, v227
	v_and_b32_e32 v243, 0xffff0000, v227
	v_pk_add_f32 v[240:241], v[240:241], v[154:155] op_sel_hi:[1,0] neg_lo:[0,1] neg_hi:[0,1]
	v_pk_add_f32 v[242:243], v[242:243], v[154:155] op_sel_hi:[1,0] neg_lo:[0,1] neg_hi:[0,1]
	v_pk_mul_f32 v[240:241], v[240:241], v[166:167] op_sel_hi:[1,0]
	v_pk_mul_f32 v[242:243], v[242:243], v[166:167] op_sel_hi:[1,0]
	v_pk_fma_f32 v[240:241], v[180:181], v[240:241], v[196:197]
	v_pk_fma_f32 v[242:243], v[182:183], v[242:243], v[198:199]
	v_pk_mul_f32 v[240:241], v[240:241], s[18:19] op_sel_hi:[1,0]
	v_pk_mul_f32 v[242:243], v[242:243], s[18:19] op_sel_hi:[1,0]
	v_pk_fma_f32 v[88:89], v[88:89], 0.5, v[240:241] op_sel_hi:[1,0,1]
	v_pk_fma_f32 v[90:91], v[90:91], 0.5, v[242:243] op_sel_hi:[1,0,1]
	global_store_dwordx4 v133, v[88:91], s[88:89] offset:64
	s_waitcnt vmcnt(23)
	v_lshlrev_b32_e32 v134, 16, v228
	v_and_b32_e32 v135, 0xffff0000, v228
	v_lshlrev_b32_e32 v136, 16, v229
	v_and_b32_e32 v137, 0xffff0000, v229
	v_pk_add_f32 v[134:135], v[134:135], v[154:155] op_sel_hi:[1,0] neg_lo:[0,1] neg_hi:[0,1]
	v_pk_add_f32 v[136:137], v[136:137], v[154:155] op_sel_hi:[1,0] neg_lo:[0,1] neg_hi:[0,1]
	v_pk_mul_f32 v[134:135], v[134:135], v[166:167] op_sel_hi:[1,0]
	v_pk_mul_f32 v[136:137], v[136:137], v[166:167] op_sel_hi:[1,0]
	v_pk_fma_f32 v[134:135], v[184:185], v[134:135], v[200:201]
	v_pk_fma_f32 v[136:137], v[186:187], v[136:137], v[202:203]
	v_pk_mul_f32 v[134:135], v[134:135], s[18:19] op_sel_hi:[1,0]
	v_pk_mul_f32 v[136:137], v[136:137], s[18:19] op_sel_hi:[1,0]
	v_pk_fma_f32 v[84:85], v[84:85], 0.5, v[134:135] op_sel_hi:[1,0,1]
	v_pk_fma_f32 v[86:87], v[86:87], 0.5, v[136:137] op_sel_hi:[1,0,1]
	global_store_dwordx4 v133, v[84:87], s[88:89] offset:512
	s_waitcnt vmcnt(23)
	v_lshlrev_b32_e32 v240, 16, v230
	v_and_b32_e32 v241, 0xffff0000, v230
	v_lshlrev_b32_e32 v242, 16, v231
	v_and_b32_e32 v243, 0xffff0000, v231
	v_pk_add_f32 v[240:241], v[240:241], v[154:155] op_sel_hi:[1,0] neg_lo:[0,1] neg_hi:[0,1]
	v_pk_add_f32 v[242:243], v[242:243], v[154:155] op_sel_hi:[1,0] neg_lo:[0,1] neg_hi:[0,1]
	v_pk_mul_f32 v[240:241], v[240:241], v[166:167] op_sel_hi:[1,0]
	v_pk_mul_f32 v[242:243], v[242:243], v[166:167] op_sel_hi:[1,0]
	v_pk_fma_f32 v[240:241], v[188:189], v[240:241], v[204:205]
	v_pk_fma_f32 v[242:243], v[190:191], v[242:243], v[206:207]
	v_pk_mul_f32 v[240:241], v[240:241], s[18:19] op_sel_hi:[1,0]
	v_pk_mul_f32 v[242:243], v[242:243], s[18:19] op_sel_hi:[1,0]
	v_pk_fma_f32 v[80:81], v[80:81], 0.5, v[240:241] op_sel_hi:[1,0,1]
	v_pk_fma_f32 v[82:83], v[82:83], 0.5, v[242:243] op_sel_hi:[1,0,1]
	global_store_dwordx4 v133, v[80:83], s[88:89] offset:576
	v_add_u32_e32 v132, 0x85000, v130
	global_load_dwordx2 v[224:225], v132, s[10:11]
	v_add_u32_e32 v149, 0x85000, v131
	global_load_dwordx2 v[226:227], v149, s[10:11]
	v_add_u32_e32 v132, 0x8d000, v130
	global_load_dwordx2 v[228:229], v132, s[10:11]
	v_add_u32_e32 v149, 0x8d000, v131
	global_load_dwordx2 v[230:231], v149, s[10:11]
	v_pk_mul_f32 v[156:157], v[156:157], s[16:17] op_sel_hi:[1,0]
	v_add_u32_e32 v133, 0x60000, v128
	v_fma_f32 v168, -v156, v156, v157
	v_max_f32_e32 v168, 0, v168
	v_add_f32_e32 v168, 0x3727c5ac, v168
	v_rsq_f32_e32 v168, v168
	s_nop 0
	s_waitcnt vmcnt(27)
	v_lshlrev_b32_e32 v134, 16, v232
	v_and_b32_e32 v135, 0xffff0000, v232
	v_lshlrev_b32_e32 v136, 16, v233
	v_and_b32_e32 v137, 0xffff0000, v233
	v_pk_add_f32 v[134:135], v[134:135], v[156:157] op_sel_hi:[1,0] neg_lo:[0,1] neg_hi:[0,1]
	v_pk_add_f32 v[136:137], v[136:137], v[156:157] op_sel_hi:[1,0] neg_lo:[0,1] neg_hi:[0,1]
	v_pk_mul_f32 v[134:135], v[134:135], v[168:169] op_sel_hi:[1,0]
	v_pk_mul_f32 v[136:137], v[136:137], v[168:169] op_sel_hi:[1,0]
	v_pk_fma_f32 v[134:135], v[176:177], v[134:135], v[192:193]
	v_pk_fma_f32 v[136:137], v[178:179], v[136:137], v[194:195]
	v_pk_mul_f32 v[134:135], v[134:135], s[18:19] op_sel_hi:[1,0]
	v_pk_mul_f32 v[136:137], v[136:137], s[18:19] op_sel_hi:[1,0]
	v_pk_fma_f32 v[76:77], v[76:77], 0.5, v[134:135] op_sel_hi:[1,0,1]
	v_pk_fma_f32 v[78:79], v[78:79], 0.5, v[136:137] op_sel_hi:[1,0,1]
	global_store_dwordx4 v133, v[76:79], s[88:89]
	s_waitcnt vmcnt(27)
	v_lshlrev_b32_e32 v240, 16, v234
	v_and_b32_e32 v241, 0xffff0000, v234
	v_lshlrev_b32_e32 v242, 16, v235
	v_and_b32_e32 v243, 0xffff0000, v235
	v_pk_add_f32 v[240:241], v[240:241], v[156:157] op_sel_hi:[1,0] neg_lo:[0,1] neg_hi:[0,1]
	v_pk_add_f32 v[242:243], v[242:243], v[156:157] op_sel_hi:[1,0] neg_lo:[0,1] neg_hi:[0,1]
	v_pk_mul_f32 v[240:241], v[240:241], v[168:169] op_sel_hi:[1,0]
	v_pk_mul_f32 v[242:243], v[242:243], v[168:169] op_sel_hi:[1,0]
	v_pk_fma_f32 v[240:241], v[180:181], v[240:241], v[196:197]
	v_pk_fma_f32 v[242:243], v[182:183], v[242:243], v[198:199]
	v_pk_mul_f32 v[240:241], v[240:241], s[18:19] op_sel_hi:[1,0]
	v_pk_mul_f32 v[242:243], v[242:243], s[18:19] op_sel_hi:[1,0]
	v_pk_fma_f32 v[72:73], v[72:73], 0.5, v[240:241] op_sel_hi:[1,0,1]
	v_pk_fma_f32 v[74:75], v[74:75], 0.5, v[242:243] op_sel_hi:[1,0,1]
	global_store_dwordx4 v133, v[72:75], s[88:89] offset:64
	s_waitcnt vmcnt(27)
; __device__ __forceinline__ float bf_lo(u32 v) { return __uint_as_float(v << 16); }
; __device__ __forceinline__ float bf_hi(u32 v) { return __uint_as_float(v & 0xFFFF0000u); }
; template <int EPI>
; __device__ __forceinline__ void gemm_phase(const u16* __restrict__ A, const u16* __restrict__ Bt, const int K,
;                                            const int nN, char* shm, const EpiArgs& ea) {
;     ...
;                   const int col = cb + bj * 128 + n * 16;
;                   f32x4 c = acc[ai][bj][m][n];
;                   float h[4];
;                   if (EPI == EPI_FFN1) {
;                     float4 rv = *(const float4*)(ea.res + (size_t)row * DM + col);
;                     h[0] = rv.x; h[1] = rv.y; h[2] = rv.z; h[3] = rv.w;
;                   } else {
;                     uint2 yv = *(const uint2*)((const char*)ea.yb + tl_off(row, col, DM >> 6));
;                     float4 gv = *(const float4*)(ea.lng + col);
;                     float4 bv = *(const float4*)(ea.lnb + col);
;                     h[0] = (bf_lo(yv.x) - mu) * rstd * gv.x + bv.x; h[1] = (bf_hi(yv.x) - mu) * rstd * gv.y + bv.y;
;                     h[2] = (bf_lo(yv.y) - mu) * rstd * gv.z + bv.z; h[3] = (bf_hi(yv.y) - mu) * rstd * gv.w + bv.w;
;                   }
;                   float y[4];
;                   if (EPI == EPI_OUT) {
;                     float4 bo = *(const float4*)(ea.bias + col);
;                     y[0] = ALPHA * h[0] + c[0] + bo.x; y[1] = ALPHA * h[1] + c[1] + bo.y;
;                     y[2] = ALPHA * h[2] + c[2] + bo.z; y[3] = ALPHA * h[3] + c[3] + bo.w;
;                   } else {
; #pragma unroll
;                     for (int j = 0; j < 4; ++j) y[j] = ALPHA * h[j] + 0.5f * c[j];
;                   }
;                   if (EPI == EPI_FFN2) {
;                     *(float4*)(ea.outf + (size_t)row * DM + col) = make_float4(y[0], y[1], y[2], y[3]);
	v_lshlrev_b32_e32 v134, 16, v236
	v_and_b32_e32 v135, 0xffff0000, v236
	v_lshlrev_b32_e32 v136, 16, v237
	v_and_b32_e32 v137, 0xffff0000, v237
	v_pk_add_f32 v[134:135], v[134:135], v[156:157] op_sel_hi:[1,0] neg_lo:[0,1] neg_hi:[0,1]
	v_pk_add_f32 v[136:137], v[136:137], v[156:157] op_sel_hi:[1,0] neg_lo:[0,1] neg_hi:[0,1]
	v_pk_mul_f32 v[134:135], v[134:135], v[168:169] op_sel_hi:[1,0]
	v_pk_mul_f32 v[136:137], v[136:137], v[168:169] op_sel_hi:[1,0]
	v_pk_fma_f32 v[134:135], v[184:185], v[134:135], v[200:201]
	v_pk_fma_f32 v[136:137], v[186:187], v[136:137], v[202:203]
	v_pk_mul_f32 v[134:135], v[134:135], s[18:19] op_sel_hi:[1,0]
	v_pk_mul_f32 v[136:137], v[136:137], s[18:19] op_sel_hi:[1,0]
	v_pk_fma_f32 v[68:69], v[68:69], 0.5, v[134:135] op_sel_hi:[1,0,1]
	v_pk_fma_f32 v[70:71], v[70:71], 0.5, v[136:137] op_sel_hi:[1,0,1]
	global_store_dwordx4 v133, v[68:71], s[88:89] offset:512
	s_waitcnt vmcnt(27)
	v_lshlrev_b32_e32 v240, 16, v238
	v_and_b32_e32 v241, 0xffff0000, v238
	v_lshlrev_b32_e32 v242, 16, v239
	v_and_b32_e32 v243, 0xffff0000, v239
	v_pk_add_f32 v[240:241], v[240:241], v[156:157] op_sel_hi:[1,0] neg_lo:[0,1] neg_hi:[0,1]
	v_pk_add_f32 v[242:243], v[242:243], v[156:157] op_sel_hi:[1,0] neg_lo:[0,1] neg_hi:[0,1]
	v_pk_mul_f32 v[240:241], v[240:241], v[168:169] op_sel_hi:[1,0]
	v_pk_mul_f32 v[242:243], v[242:243], v[168:169] op_sel_hi:[1,0]
	v_pk_fma_f32 v[240:241], v[188:189], v[240:241], v[204:205]
	v_pk_fma_f32 v[242:243], v[190:191], v[242:243], v[206:207]
	v_pk_mul_f32 v[240:241], v[240:241], s[18:19] op_sel_hi:[1,0]
	v_pk_mul_f32 v[242:243], v[242:243], s[18:19] op_sel_hi:[1,0]
	v_pk_fma_f32 v[64:65], v[64:65], 0.5, v[240:241] op_sel_hi:[1,0,1]
	v_pk_fma_f32 v[66:67], v[66:67], 0.5, v[242:243] op_sel_hi:[1,0,1]
	global_store_dwordx4 v133, v[64:67], s[88:89] offset:576
	v_add_u32_e32 v132, 0x85800, v130
	global_load_dwordx2 v[232:233], v132, s[10:11]
	v_add_u32_e32 v149, 0x85800, v131
	global_load_dwordx2 v[234:235], v149, s[10:11]
	v_add_u32_e32 v132, 0x8d800, v130
	global_load_dwordx2 v[236:237], v132, s[10:11]
	v_add_u32_e32 v149, 0x8d800, v131
	global_load_dwordx2 v[238:239], v149, s[10:11]
	v_pk_mul_f32 v[158:159], v[158:159], s[16:17] op_sel_hi:[1,0]
	v_add_u32_e32 v133, 0x100000, v128
	v_fma_f32 v166, -v158, v158, v159
	v_max_f32_e32 v166, 0, v166
	v_add_f32_e32 v166, 0x3727c5ac, v166
	v_rsq_f32_e32 v166, v166
	s_nop 0
	s_waitcnt vmcnt(27)
	v_lshlrev_b32_e32 v134, 16, v208
	v_and_b32_e32 v135, 0xffff0000, v208
	v_lshlrev_b32_e32 v136, 16, v209
	v_and_b32_e32 v137, 0xffff0000, v209
	v_pk_add_f32 v[134:135], v[134:135], v[158:159] op_sel_hi:[1,0] neg_lo:[0,1] neg_hi:[0,1]
	v_pk_add_f32 v[136:137], v[136:137], v[158:159] op_sel_hi:[1,0] neg_lo:[0,1] neg_hi:[0,1]
	v_pk_mul_f32 v[134:135], v[134:135], v[166:167] op_sel_hi:[1,0]
	v_pk_mul_f32 v[136:137], v[136:137], v[166:167] op_sel_hi:[1,0]
	v_pk_fma_f32 v[134:135], v[176:177], v[134:135], v[192:193]
	v_pk_fma_f32 v[136:137], v[178:179], v[136:137], v[194:195]
	v_pk_mul_f32 v[134:135], v[134:135], s[18:19] op_sel_hi:[1,0]
	v_pk_mul_f32 v[136:137], v[136:137], s[18:19] op_sel_hi:[1,0]
	v_pk_fma_f32 v[60:61], v[60:61], 0.5, v[134:135] op_sel_hi:[1,0,1]
	v_pk_fma_f32 v[62:63], v[62:63], 0.5, v[136:137] op_sel_hi:[1,0,1]
	global_store_dwordx4 v133, v[60:63], s[88:89]
	s_waitcnt vmcnt(27)
	v_lshlrev_b32_e32 v240, 16, v210
	v_and_b32_e32 v241, 0xffff0000, v210
	v_lshlrev_b32_e32 v242, 16, v211
	v_and_b32_e32 v243, 0xffff0000, v211
	v_pk_add_f32 v[240:241], v[240:241], v[158:159] op_sel_hi:[1,0] neg_lo:[0,1] neg_hi:[0,1]
	v_pk_add_f32 v[242:243], v[242:243], v[158:159] op_sel_hi:[1,0] neg_lo:[0,1] neg_hi:[0,1]
	v_pk_mul_f32 v[240:241], v[240:241], v[166:167] op_sel_hi:[1,0]
	v_pk_mul_f32 v[242:243], v[242:243], v[166:167] op_sel_hi:[1,0]
	v_pk_fma_f32 v[240:241], v[180:181], v[240:241], v[196:197]
	v_pk_fma_f32 v[242:243], v[182:183], v[242:243], v[198:199]
	v_pk_mul_f32 v[240:241], v[240:241], s[18:19] op_sel_hi:[1,0]
	v_pk_mul_f32 v[242:243], v[242:243], s[18:19] op_sel_hi:[1,0]
	v_pk_fma_f32 v[56:57], v[56:57], 0.5, v[240:241] op_sel_hi:[1,0,1]
	v_pk_fma_f32 v[58:59], v[58:59], 0.5, v[242:243] op_sel_hi:[1,0,1]
	global_store_dwordx4 v133, v[56:59], s[88:89] offset:64
	s_waitcnt vmcnt(27)
	v_lshlrev_b32_e32 v134, 16, v212
	v_and_b32_e32 v135, 0xffff0000, v212
	v_lshlrev_b32_e32 v136, 16, v213
	v_and_b32_e32 v137, 0xffff0000, v213
	v_pk_add_f32 v[134:135], v[134:135], v[158:159] op_sel_hi:[1,0] neg_lo:[0,1] neg_hi:[0,1]
	v_pk_add_f32 v[136:137], v[136:137], v[158:159] op_sel_hi:[1,0] neg_lo:[0,1] neg_hi:[0,1]
	v_pk_mul_f32 v[134:135], v[134:135], v[166:167] op_sel_hi:[1,0]
	v_pk_mul_f32 v[136:137], v[136:137], v[166:167] op_sel_hi:[1,0]
	v_pk_fma_f32 v[134:135], v[184:185], v[134:135], v[200:201]
	v_pk_fma_f32 v[136:137], v[186:187], v[136:137], v[202:203]
	v_pk_mul_f32 v[134:135], v[134:135], s[18:19] op_sel_hi:[1,0]
	v_pk_mul_f32 v[136:137], v[136:137], s[18:19] op_sel_hi:[1,0]
	v_pk_fma_f32 v[52:53], v[52:53], 0.5, v[134:135] op_sel_hi:[1,0,1]
	v_pk_fma_f32 v[54:55], v[54:55], 0.5, v[136:137] op_sel_hi:[1,0,1]
	global_store_dwordx4 v133, v[52:55], s[88:89] offset:512
	s_waitcnt vmcnt(27)
; __device__ __forceinline__ float bf_lo(u32 v) { return __uint_as_float(v << 16); }
; __device__ __forceinline__ float bf_hi(u32 v) { return __uint_as_float(v & 0xFFFF0000u); }
; template <int EPI>
; __device__ __forceinline__ void gemm_phase(const u16* __restrict__ A, const u16* __restrict__ Bt, const int K,
;                                            const int nN, char* shm, const EpiArgs& ea) {
;     ...
;                   const int col = cb + bj * 128 + n * 16;
;                   f32x4 c = acc[ai][bj][m][n];
;                   float h[4];
;                   if (EPI == EPI_FFN1) {
;                     float4 rv = *(const float4*)(ea.res + (size_t)row * DM + col);
;                     h[0] = rv.x; h[1] = rv.y; h[2] = rv.z; h[3] = rv.w;
;                   } else {
;                     uint2 yv = *(const uint2*)((const char*)ea.yb + tl_off(row, col, DM >> 6));
;                     float4 gv = *(const float4*)(ea.lng + col);
;                     float4 bv = *(const float4*)(ea.lnb + col);
;                     h[0] = (bf_lo(yv.x) - mu) * rstd * gv.x + bv.x; h[1] = (bf_hi(yv.x) - mu) * rstd * gv.y + bv.y;
;                     h[2] = (bf_lo(yv.y) - mu) * rstd * gv.z + bv.z; h[3] = (bf_hi(yv.y) - mu) * rstd * gv.w + bv.w;
;                   }
;                   float y[4];
;                   if (EPI == EPI_OUT) {
;                     float4 bo = *(const float4*)(ea.bias + col);
;                     y[0] = ALPHA * h[0] + c[0] + bo.x; y[1] = ALPHA * h[1] + c[1] + bo.y;
;                     y[2] = ALPHA * h[2] + c[2] + bo.z; y[3] = ALPHA * h[3] + c[3] + bo.w;
;                   } else {
; #pragma unroll
;                     for (int j = 0; j < 4; ++j) y[j] = ALPHA * h[j] + 0.5f * c[j];
;                   }
;                   if (EPI == EPI_FFN2) {
;                     *(float4*)(ea.outf + (size_t)row * DM + col) = make_float4(y[0], y[1], y[2], y[3]);
	v_lshlrev_b32_e32 v240, 16, v214
	v_and_b32_e32 v241, 0xffff0000, v214
	v_lshlrev_b32_e32 v242, 16, v215
	v_and_b32_e32 v243, 0xffff0000, v215
	v_pk_add_f32 v[240:241], v[240:241], v[158:159] op_sel_hi:[1,0] neg_lo:[0,1] neg_hi:[0,1]
	v_pk_add_f32 v[242:243], v[242:243], v[158:159] op_sel_hi:[1,0] neg_lo:[0,1] neg_hi:[0,1]
	v_pk_mul_f32 v[240:241], v[240:241], v[166:167] op_sel_hi:[1,0]
	v_pk_mul_f32 v[242:243], v[242:243], v[166:167] op_sel_hi:[1,0]
	v_pk_fma_f32 v[240:241], v[188:189], v[240:241], v[204:205]
	v_pk_fma_f32 v[242:243], v[190:191], v[242:243], v[206:207]
	v_pk_mul_f32 v[240:241], v[240:241], s[18:19] op_sel_hi:[1,0]
	v_pk_mul_f32 v[242:243], v[242:243], s[18:19] op_sel_hi:[1,0]
	v_pk_fma_f32 v[48:49], v[48:49], 0.5, v[240:241] op_sel_hi:[1,0,1]
	v_pk_fma_f32 v[50:51], v[50:51], 0.5, v[242:243] op_sel_hi:[1,0,1]
	global_store_dwordx4 v133, v[48:51], s[88:89] offset:576
	v_pk_mul_f32 v[160:161], v[160:161], s[16:17] op_sel_hi:[1,0]
	v_add_u32_e32 v133, 0x120000, v128
	v_fma_f32 v168, -v160, v160, v161
	v_max_f32_e32 v168, 0, v168
	v_add_f32_e32 v168, 0x3727c5ac, v168
	v_rsq_f32_e32 v168, v168
	s_nop 0
	s_waitcnt vmcnt(23)
	v_lshlrev_b32_e32 v134, 16, v216
	v_and_b32_e32 v135, 0xffff0000, v216
	v_lshlrev_b32_e32 v136, 16, v217
	v_and_b32_e32 v137, 0xffff0000, v217
	v_pk_add_f32 v[134:135], v[134:135], v[160:161] op_sel_hi:[1,0] neg_lo:[0,1] neg_hi:[0,1]
	v_pk_add_f32 v[136:137], v[136:137], v[160:161] op_sel_hi:[1,0] neg_lo:[0,1] neg_hi:[0,1]
	v_pk_mul_f32 v[134:135], v[134:135], v[168:169] op_sel_hi:[1,0]
	v_pk_mul_f32 v[136:137], v[136:137], v[168:169] op_sel_hi:[1,0]
	v_pk_fma_f32 v[134:135], v[176:177], v[134:135], v[192:193]
	v_pk_fma_f32 v[136:137], v[178:179], v[136:137], v[194:195]
	v_pk_mul_f32 v[134:135], v[134:135], s[18:19] op_sel_hi:[1,0]
	v_pk_mul_f32 v[136:137], v[136:137], s[18:19] op_sel_hi:[1,0]
	v_pk_fma_f32 v[44:45], v[44:45], 0.5, v[134:135] op_sel_hi:[1,0,1]
	v_pk_fma_f32 v[46:47], v[46:47], 0.5, v[136:137] op_sel_hi:[1,0,1]
	global_store_dwordx4 v133, v[44:47], s[88:89]
	s_waitcnt vmcnt(23)
	v_lshlrev_b32_e32 v240, 16, v218
	v_and_b32_e32 v241, 0xffff0000, v218
	v_lshlrev_b32_e32 v242, 16, v219
	v_and_b32_e32 v243, 0xffff0000, v219
	v_pk_add_f32 v[240:241], v[240:241], v[160:161] op_sel_hi:[1,0] neg_lo:[0,1] neg_hi:[0,1]
	v_pk_add_f32 v[242:243], v[242:243], v[160:161] op_sel_hi:[1,0] neg_lo:[0,1] neg_hi:[0,1]
	v_pk_mul_f32 v[240:241], v[240:241], v[168:169] op_sel_hi:[1,0]
	v_pk_mul_f32 v[242:243], v[242:243], v[168:169] op_sel_hi:[1,0]
	v_pk_fma_f32 v[240:241], v[180:181], v[240:241], v[196:197]
	v_pk_fma_f32 v[242:243], v[182:183], v[242:243], v[198:199]
	v_pk_mul_f32 v[240:241], v[240:241], s[18:19] op_sel_hi:[1,0]
	v_pk_mul_f32 v[242:243], v[242:243], s[18:19] op_sel_hi:[1,0]
	v_pk_fma_f32 v[40:41], v[40:41], 0.5, v[240:241] op_sel_hi:[1,0,1]
	v_pk_fma_f32 v[42:43], v[42:43], 0.5, v[242:243] op_sel_hi:[1,0,1]
	global_store_dwordx4 v133, v[40:43], s[88:89] offset:64
	s_waitcnt vmcnt(23)
	v_lshlrev_b32_e32 v134, 16, v220
	v_and_b32_e32 v135, 0xffff0000, v220
	v_lshlrev_b32_e32 v136, 16, v221
	v_and_b32_e32 v137, 0xffff0000, v221
	v_pk_add_f32 v[134:135], v[134:135], v[160:161] op_sel_hi:[1,0] neg_lo:[0,1] neg_hi:[0,1]
	v_pk_add_f32 v[136:137], v[136:137], v[160:161] op_sel_hi:[1,0] neg_lo:[0,1] neg_hi:[0,1]
	v_pk_mul_f32 v[134:135], v[134:135], v[168:169] op_sel_hi:[1,0]
	v_pk_mul_f32 v[136:137], v[136:137], v[168:169] op_sel_hi:[1,0]
	v_pk_fma_f32 v[134:135], v[184:185], v[134:135], v[200:201]
	v_pk_fma_f32 v[136:137], v[186:187], v[136:137], v[202:203]
	v_pk_mul_f32 v[134:135], v[134:135], s[18:19] op_sel_hi:[1,0]
	v_pk_mul_f32 v[136:137], v[136:137], s[18:19] op_sel_hi:[1,0]
	v_pk_fma_f32 v[36:37], v[36:37], 0.5, v[134:135] op_sel_hi:[1,0,1]
	v_pk_fma_f32 v[38:39], v[38:39], 0.5, v[136:137] op_sel_hi:[1,0,1]
	global_store_dwordx4 v133, v[36:39], s[88:89] offset:512
	s_waitcnt vmcnt(23)
	v_lshlrev_b32_e32 v240, 16, v222
	v_and_b32_e32 v241, 0xffff0000, v222
	v_lshlrev_b32_e32 v242, 16, v223
	v_and_b32_e32 v243, 0xffff0000, v223
	v_pk_add_f32 v[240:241], v[240:241], v[160:161] op_sel_hi:[1,0] neg_lo:[0,1] neg_hi:[0,1]
	v_pk_add_f32 v[242:243], v[242:243], v[160:161] op_sel_hi:[1,0] neg_lo:[0,1] neg_hi:[0,1]
	v_pk_mul_f32 v[240:241], v[240:241], v[168:169] op_sel_hi:[1,0]
	v_pk_mul_f32 v[242:243], v[242:243], v[168:169] op_sel_hi:[1,0]
	v_pk_fma_f32 v[240:241], v[188:189], v[240:241], v[204:205]
	v_pk_fma_f32 v[242:243], v[190:191], v[242:243], v[206:207]
	v_pk_mul_f32 v[240:241], v[240:241], s[18:19] op_sel_hi:[1,0]
	v_pk_mul_f32 v[242:243], v[242:243], s[18:19] op_sel_hi:[1,0]
	v_pk_fma_f32 v[32:33], v[32:33], 0.5, v[240:241] op_sel_hi:[1,0,1]
	v_pk_fma_f32 v[34:35], v[34:35], 0.5, v[242:243] op_sel_hi:[1,0,1]
	global_store_dwordx4 v133, v[32:35], s[88:89] offset:576
	v_pk_mul_f32 v[162:163], v[162:163], s[16:17] op_sel_hi:[1,0]
	v_add_u32_e32 v133, 0x140000, v128
	v_fma_f32 v166, -v162, v162, v163
	v_max_f32_e32 v166, 0, v166
	v_add_f32_e32 v166, 0x3727c5ac, v166
	v_rsq_f32_e32 v166, v166
	s_nop 0
	s_waitcnt vmcnt(19)
	v_lshlrev_b32_e32 v134, 16, v224
	v_and_b32_e32 v135, 0xffff0000, v224
	v_lshlrev_b32_e32 v136, 16, v225
	v_and_b32_e32 v137, 0xffff0000, v225
	v_pk_add_f32 v[134:135], v[134:135], v[162:163] op_sel_hi:[1,0] neg_lo:[0,1] neg_hi:[0,1]
	v_pk_add_f32 v[136:137], v[136:137], v[162:163] op_sel_hi:[1,0] neg_lo:[0,1] neg_hi:[0,1]
	v_pk_mul_f32 v[134:135], v[134:135], v[166:167] op_sel_hi:[1,0]
	v_pk_mul_f32 v[136:137], v[136:137], v[166:167] op_sel_hi:[1,0]
	v_pk_fma_f32 v[134:135], v[176:177], v[134:135], v[192:193]
	v_pk_fma_f32 v[136:137], v[178:179], v[136:137], v[194:195]
	v_pk_mul_f32 v[134:135], v[134:135], s[18:19] op_sel_hi:[1,0]
	v_pk_mul_f32 v[136:137], v[136:137], s[18:19] op_sel_hi:[1,0]
	v_pk_fma_f32 v[28:29], v[28:29], 0.5, v[134:135] op_sel_hi:[1,0,1]
	v_pk_fma_f32 v[30:31], v[30:31], 0.5, v[136:137] op_sel_hi:[1,0,1]
	global_store_dwordx4 v133, v[28:31], s[88:89]
	s_waitcnt vmcnt(19)
; __device__ __forceinline__ float bf_lo(u32 v) { return __uint_as_float(v << 16); }
; __device__ __forceinline__ float bf_hi(u32 v) { return __uint_as_float(v & 0xFFFF0000u); }
; template <int EPI>
; __device__ __forceinline__ void gemm_phase(const u16* __restrict__ A, const u16* __restrict__ Bt, const int K,
;                                            const int nN, char* shm, const EpiArgs& ea) {
;     ...
;                   const int col = cb + bj * 128 + n * 16;
;                   f32x4 c = acc[ai][bj][m][n];
;                   float h[4];
;                   if (EPI == EPI_FFN1) {
;                     float4 rv = *(const float4*)(ea.res + (size_t)row * DM + col);
;                     h[0] = rv.x; h[1] = rv.y; h[2] = rv.z; h[3] = rv.w;
;                   } else {
;                     uint2 yv = *(const uint2*)((const char*)ea.yb + tl_off(row, col, DM >> 6));
;                     float4 gv = *(const float4*)(ea.lng + col);
;                     float4 bv = *(const float4*)(ea.lnb + col);
;                     h[0] = (bf_lo(yv.x) - mu) * rstd * gv.x + bv.x; h[1] = (bf_hi(yv.x) - mu) * rstd * gv.y + bv.y;
;                     h[2] = (bf_lo(yv.y) - mu) * rstd * gv.z + bv.z; h[3] = (bf_hi(yv.y) - mu) * rstd * gv.w + bv.w;
;                   }
;                   float y[4];
;                   if (EPI == EPI_OUT) {
;                     float4 bo = *(const float4*)(ea.bias + col);
;                     y[0] = ALPHA * h[0] + c[0] + bo.x; y[1] = ALPHA * h[1] + c[1] + bo.y;
;                     y[2] = ALPHA * h[2] + c[2] + bo.z; y[3] = ALPHA * h[3] + c[3] + bo.w;
;                   } else {
; #pragma unroll
;                     for (int j = 0; j < 4; ++j) y[j] = ALPHA * h[j] + 0.5f * c[j];
;                   }
;                   if (EPI == EPI_FFN2) {
;                     *(float4*)(ea.outf + (size_t)row * DM + col) = make_float4(y[0], y[1], y[2], y[3]);
	v_lshlrev_b32_e32 v240, 16, v226
	v_and_b32_e32 v241, 0xffff0000, v226
	v_lshlrev_b32_e32 v242, 16, v227
	v_and_b32_e32 v243, 0xffff0000, v227
	v_pk_add_f32 v[240:241], v[240:241], v[162:163] op_sel_hi:[1,0] neg_lo:[0,1] neg_hi:[0,1]
	v_pk_add_f32 v[242:243], v[242:243], v[162:163] op_sel_hi:[1,0] neg_lo:[0,1] neg_hi:[0,1]
	v_pk_mul_f32 v[240:241], v[240:241], v[166:167] op_sel_hi:[1,0]
	v_pk_mul_f32 v[242:243], v[242:243], v[166:167] op_sel_hi:[1,0]
	v_pk_fma_f32 v[240:241], v[180:181], v[240:241], v[196:197]
	v_pk_fma_f32 v[242:243], v[182:183], v[242:243], v[198:199]
	v_pk_mul_f32 v[240:241], v[240:241], s[18:19] op_sel_hi:[1,0]
	v_pk_mul_f32 v[242:243], v[242:243], s[18:19] op_sel_hi:[1,0]
	v_pk_fma_f32 v[24:25], v[24:25], 0.5, v[240:241] op_sel_hi:[1,0,1]
	v_pk_fma_f32 v[26:27], v[26:27], 0.5, v[242:243] op_sel_hi:[1,0,1]
	global_store_dwordx4 v133, v[24:27], s[88:89] offset:64
	s_waitcnt vmcnt(19)
	v_lshlrev_b32_e32 v134, 16, v228
	v_and_b32_e32 v135, 0xffff0000, v228
	v_lshlrev_b32_e32 v136, 16, v229
	v_and_b32_e32 v137, 0xffff0000, v229
	v_pk_add_f32 v[134:135], v[134:135], v[162:163] op_sel_hi:[1,0] neg_lo:[0,1] neg_hi:[0,1]
	v_pk_add_f32 v[136:137], v[136:137], v[162:163] op_sel_hi:[1,0] neg_lo:[0,1] neg_hi:[0,1]
	v_pk_mul_f32 v[134:135], v[134:135], v[166:167] op_sel_hi:[1,0]
	v_pk_mul_f32 v[136:137], v[136:137], v[166:167] op_sel_hi:[1,0]
	v_pk_fma_f32 v[134:135], v[184:185], v[134:135], v[200:201]
	v_pk_fma_f32 v[136:137], v[186:187], v[136:137], v[202:203]
	v_pk_mul_f32 v[134:135], v[134:135], s[18:19] op_sel_hi:[1,0]
	v_pk_mul_f32 v[136:137], v[136:137], s[18:19] op_sel_hi:[1,0]
	v_pk_fma_f32 v[20:21], v[20:21], 0.5, v[134:135] op_sel_hi:[1,0,1]
	v_pk_fma_f32 v[22:23], v[22:23], 0.5, v[136:137] op_sel_hi:[1,0,1]
	global_store_dwordx4 v133, v[20:23], s[88:89] offset:512
	s_waitcnt vmcnt(19)
	v_lshlrev_b32_e32 v240, 16, v230
	v_and_b32_e32 v241, 0xffff0000, v230
	v_lshlrev_b32_e32 v242, 16, v231
	v_and_b32_e32 v243, 0xffff0000, v231
	v_pk_add_f32 v[240:241], v[240:241], v[162:163] op_sel_hi:[1,0] neg_lo:[0,1] neg_hi:[0,1]
	v_pk_add_f32 v[242:243], v[242:243], v[162:163] op_sel_hi:[1,0] neg_lo:[0,1] neg_hi:[0,1]
	v_pk_mul_f32 v[240:241], v[240:241], v[166:167] op_sel_hi:[1,0]
	v_pk_mul_f32 v[242:243], v[242:243], v[166:167] op_sel_hi:[1,0]
	v_pk_fma_f32 v[240:241], v[188:189], v[240:241], v[204:205]
	v_pk_fma_f32 v[242:243], v[190:191], v[242:243], v[206:207]
	v_pk_mul_f32 v[240:241], v[240:241], s[18:19] op_sel_hi:[1,0]
	v_pk_mul_f32 v[242:243], v[242:243], s[18:19] op_sel_hi:[1,0]
	v_pk_fma_f32 v[16:17], v[16:17], 0.5, v[240:241] op_sel_hi:[1,0,1]
	v_pk_fma_f32 v[18:19], v[18:19], 0.5, v[242:243] op_sel_hi:[1,0,1]
	global_store_dwordx4 v133, v[16:19], s[88:89] offset:576
	v_pk_mul_f32 v[164:165], v[164:165], s[16:17] op_sel_hi:[1,0]
	v_add_u32_e32 v133, 0x160000, v128
	v_fma_f32 v168, -v164, v164, v165
	v_max_f32_e32 v168, 0, v168
	v_add_f32_e32 v168, 0x3727c5ac, v168
	v_rsq_f32_e32 v168, v168
	s_nop 0
	s_waitcnt vmcnt(15)
	v_lshlrev_b32_e32 v134, 16, v232
	v_and_b32_e32 v135, 0xffff0000, v232
	v_lshlrev_b32_e32 v136, 16, v233
	v_and_b32_e32 v137, 0xffff0000, v233
	v_pk_add_f32 v[134:135], v[134:135], v[164:165] op_sel_hi:[1,0] neg_lo:[0,1] neg_hi:[0,1]
	v_pk_add_f32 v[136:137], v[136:137], v[164:165] op_sel_hi:[1,0] neg_lo:[0,1] neg_hi:[0,1]
	v_pk_mul_f32 v[134:135], v[134:135], v[168:169] op_sel_hi:[1,0]
	v_pk_mul_f32 v[136:137], v[136:137], v[168:169] op_sel_hi:[1,0]
	v_pk_fma_f32 v[134:135], v[176:177], v[134:135], v[192:193]
	v_pk_fma_f32 v[136:137], v[178:179], v[136:137], v[194:195]
	v_pk_mul_f32 v[134:135], v[134:135], s[18:19] op_sel_hi:[1,0]
	v_pk_mul_f32 v[136:137], v[136:137], s[18:19] op_sel_hi:[1,0]
	v_pk_fma_f32 v[12:13], v[12:13], 0.5, v[134:135] op_sel_hi:[1,0,1]
	v_pk_fma_f32 v[14:15], v[14:15], 0.5, v[136:137] op_sel_hi:[1,0,1]
	global_store_dwordx4 v133, v[12:15], s[88:89]
	s_waitcnt vmcnt(15)
	v_lshlrev_b32_e32 v240, 16, v234
	v_and_b32_e32 v241, 0xffff0000, v234
	v_lshlrev_b32_e32 v242, 16, v235
	v_and_b32_e32 v243, 0xffff0000, v235
	v_pk_add_f32 v[240:241], v[240:241], v[164:165] op_sel_hi:[1,0] neg_lo:[0,1] neg_hi:[0,1]
	v_pk_add_f32 v[242:243], v[242:243], v[164:165] op_sel_hi:[1,0] neg_lo:[0,1] neg_hi:[0,1]
	v_pk_mul_f32 v[240:241], v[240:241], v[168:169] op_sel_hi:[1,0]
	v_pk_mul_f32 v[242:243], v[242:243], v[168:169] op_sel_hi:[1,0]
	v_pk_fma_f32 v[240:241], v[180:181], v[240:241], v[196:197]
	v_pk_fma_f32 v[242:243], v[182:183], v[242:243], v[198:199]
	v_pk_mul_f32 v[240:241], v[240:241], s[18:19] op_sel_hi:[1,0]
	v_pk_mul_f32 v[242:243], v[242:243], s[18:19] op_sel_hi:[1,0]
	v_pk_fma_f32 v[8:9], v[8:9], 0.5, v[240:241] op_sel_hi:[1,0,1]
	v_pk_fma_f32 v[10:11], v[10:11], 0.5, v[242:243] op_sel_hi:[1,0,1]
	global_store_dwordx4 v133, v[8:11], s[88:89] offset:64
	s_waitcnt vmcnt(15)
	v_lshlrev_b32_e32 v134, 16, v236
	v_and_b32_e32 v135, 0xffff0000, v236
	v_lshlrev_b32_e32 v136, 16, v237
	v_and_b32_e32 v137, 0xffff0000, v237
	v_pk_add_f32 v[134:135], v[134:135], v[164:165] op_sel_hi:[1,0] neg_lo:[0,1] neg_hi:[0,1]
	v_pk_add_f32 v[136:137], v[136:137], v[164:165] op_sel_hi:[1,0] neg_lo:[0,1] neg_hi:[0,1]
	v_pk_mul_f32 v[134:135], v[134:135], v[168:169] op_sel_hi:[1,0]
	v_pk_mul_f32 v[136:137], v[136:137], v[168:169] op_sel_hi:[1,0]
	v_pk_fma_f32 v[134:135], v[184:185], v[134:135], v[200:201]
	v_pk_fma_f32 v[136:137], v[186:187], v[136:137], v[202:203]
	v_pk_mul_f32 v[134:135], v[134:135], s[18:19] op_sel_hi:[1,0]
	v_pk_mul_f32 v[136:137], v[136:137], s[18:19] op_sel_hi:[1,0]
	v_pk_fma_f32 v[4:5], v[4:5], 0.5, v[134:135] op_sel_hi:[1,0,1]
	v_pk_fma_f32 v[6:7], v[6:7], 0.5, v[136:137] op_sel_hi:[1,0,1]
	global_store_dwordx4 v133, v[4:7], s[88:89] offset:512
	s_waitcnt vmcnt(15)
	v_lshlrev_b32_e32 v240, 16, v238
	v_and_b32_e32 v241, 0xffff0000, v238
	v_lshlrev_b32_e32 v242, 16, v239
	v_and_b32_e32 v243, 0xffff0000, v239
	v_pk_add_f32 v[240:241], v[240:241], v[164:165] op_sel_hi:[1,0] neg_lo:[0,1] neg_hi:[0,1]
	v_pk_add_f32 v[242:243], v[242:243], v[164:165] op_sel_hi:[1,0] neg_lo:[0,1] neg_hi:[0,1]
	v_pk_mul_f32 v[240:241], v[240:241], v[168:169] op_sel_hi:[1,0]
	v_pk_mul_f32 v[242:243], v[242:243], v[168:169] op_sel_hi:[1,0]
	v_pk_fma_f32 v[240:241], v[188:189], v[240:241], v[204:205]
	v_pk_fma_f32 v[242:243], v[190:191], v[242:243], v[206:207]
	v_pk_mul_f32 v[240:241], v[240:241], s[18:19] op_sel_hi:[1,0]
	v_pk_mul_f32 v[242:243], v[242:243], s[18:19] op_sel_hi:[1,0]
	v_pk_fma_f32 v[0:1], v[0:1], 0.5, v[240:241] op_sel_hi:[1,0,1]
	v_pk_fma_f32 v[2:3], v[2:3], 0.5, v[242:243] op_sel_hi:[1,0,1]
	global_store_dwordx4 v133, v[0:3], s[88:89] offset:576
	s_mov_b32 s33, s46
	s_mov_b32 s47, s45
	s_andn2_b64 vcc, exec, s[20:21]
	s_cbranch_vccz .LBB0_636
